# grid-barrier census: the 16 per-XCC counter loads issued back to back with one wait (were 16 serial sc1 round trips before the first barrier)
# speedup vs baseline: 1.0020x; 1.0020x over previous
; __device__ __forceinline__ unsigned xb_ld(unsigned* p)              { return __hip_atomic_load(p, __ATOMIC_RELAXED, __HIP_MEMORY_SCOPE_AGENT); }
; __device__ __forceinline__ void xcd_barrier_complete(unsigned* bar, unsigned x, unsigned& nloc, unsigned& nx) {
;     ...
;     for (;;) {
;         sum = 0u; cnt = 0u; mine = 0u;
; #pragma unroll
;         for (unsigned j = 0; j < 16; ++j) { const unsigned c = xb_ld(&bar[XB_XCNT(j)]); sum += c; cnt += (c > 0u) ? 1u : 0u; mine = (j == x) ? c : mine; }
;         if (sum == G) break;
;         __builtin_amdgcn_s_sleep(1);
;         if ((++sp & 255u) == 0u) { if (xb_ld(&bar[XB_TMO])) break; if (sp > XB_SPIN_CAP) { atomicAdd(&bar[XB_TMO], 1u); break; } }
;     }
.LBB0_799:
	v_readlane_b32 s2, v253, 3
	v_readlane_b32 s3, v253, 4
	s_mov_b64 s[4:5], -1
	s_nop 3
	global_load_dword v0, v2, s[2:3] sc1
	v_readlane_b32 s2, v253, 5
	v_readlane_b32 s3, v253, 6
	s_nop 4
	global_load_dword v1, v2, s[2:3] sc1
	v_readlane_b32 s2, v253, 7
	v_readlane_b32 s3, v253, 8
	s_nop 4
	global_load_dword v3, v2, s[2:3] sc1
	v_readlane_b32 s2, v253, 9
	v_readlane_b32 s3, v253, 10
	s_nop 4
	global_load_dword v4, v2, s[2:3] sc1
	v_readlane_b32 s2, v253, 11
	v_readlane_b32 s3, v253, 12
	s_nop 4
	global_load_dword v5, v2, s[2:3] sc1
	v_readlane_b32 s2, v253, 13
	v_readlane_b32 s3, v253, 14
	s_nop 4
	global_load_dword v6, v2, s[2:3] sc1
	v_readlane_b32 s2, v253, 15
	v_readlane_b32 s3, v253, 16
	s_nop 4
	global_load_dword v7, v2, s[2:3] sc1
	v_readlane_b32 s2, v253, 17
	v_readlane_b32 s3, v253, 18
	s_nop 4
	global_load_dword v8, v2, s[2:3] sc1
	v_readlane_b32 s2, v253, 19
	v_readlane_b32 s3, v253, 20
	s_nop 4
	global_load_dword v9, v2, s[2:3] sc1
	v_readlane_b32 s2, v253, 21
	v_readlane_b32 s3, v253, 22
	s_nop 4
	global_load_dword v10, v2, s[2:3] sc1
	v_readlane_b32 s2, v253, 23
	v_readlane_b32 s3, v253, 24
	s_nop 4
	global_load_dword v11, v2, s[2:3] sc1
	v_readlane_b32 s2, v253, 25
	v_readlane_b32 s3, v253, 26
	s_nop 4
	global_load_dword v12, v2, s[2:3] sc1
	v_readlane_b32 s2, v253, 27
	v_readlane_b32 s3, v253, 28
	s_nop 4
	global_load_dword v13, v2, s[2:3] sc1
	v_readlane_b32 s2, v253, 29
	v_readlane_b32 s3, v253, 30
	s_nop 4
	global_load_dword v14, v2, s[2:3] sc1
	v_readlane_b32 s2, v253, 31
	v_readlane_b32 s3, v253, 32
	s_nop 4
	global_load_dword v15, v2, s[2:3] sc1
	v_readlane_b32 s2, v253, 33
	v_readlane_b32 s3, v253, 34
	s_nop 4
	global_load_dword v16, v2, s[2:3] sc1
	s_mov_b64 s[2:3], -1
	s_waitcnt vmcnt(0)
	v_add_u32_e32 v17, v1, v0
	v_add_u32_e32 v17, v17, v3
	v_add_u32_e32 v17, v17, v4
	v_add_u32_e32 v17, v17, v5
	v_add_u32_e32 v17, v17, v6
	v_add_u32_e32 v17, v17, v7
	v_add_u32_e32 v17, v17, v8
	v_add_u32_e32 v17, v17, v9
	v_add_u32_e32 v17, v17, v10
	v_add_u32_e32 v17, v17, v11
	v_add_u32_e32 v17, v17, v12
	v_add_u32_e32 v17, v17, v13
	v_add_u32_e32 v17, v17, v14
	v_add_u32_e32 v17, v17, v15
	v_add_u32_e32 v17, v17, v16
	v_cmp_eq_u32_e32 vcc, s8, v17
	s_cbranch_vccnz .LBB0_798
	s_and_b32 s2, s9, 0xff
	s_cmp_eq_u32 s2, 0
	s_mov_b64 s[2:3], -1
	s_mov_b64 s[6:7], -1
	s_sleep 1
	s_cbranch_scc1 .LBB0_803
	s_and_b64 vcc, exec, s[6:7]
	s_cbranch_vccz .LBB0_798
